# rwkv tiles: the per-chunk stash waits only for the prefetch loads (counted vmcnt), not for the y/g stores issued during the scan
# speedup vs baseline: 1.0782x; 1.0187x over previous
.LBB0_1436:
	s_and_b64 s[50:51], s[42:43], s[48:49]
	s_and_saveexec_b64 s[48:49], s[50:51]
	s_cbranch_execz .LBB0_1410
	s_waitcnt vmcnt(4)
	ds_write_b128 v104, v[32:35]
	ds_write_b128 v105, v[28:31]
	ds_write_b128 v106, v[36:39]
	s_and_saveexec_b64 s[50:51], s[44:45]
	ds_write_b128 v120, v[40:43]
	s_or_b64 exec, exec, s[50:51]
	ds_write_b128 v104, v[44:47] offset:13056
	ds_write_b128 v105, v[48:51] offset:13056
	ds_write_b128 v106, v[52:55] offset:13056
	s_and_b64 exec, exec, s[46:47]
	s_cbranch_execz .LBB0_1410
	ds_write_b128 v120, v[56:59] offset:13056
	s_branch .LBB0_1410

.LBB0_1491:
	s_and_b64 s[54:55], s[42:43], s[54:55]
	s_and_saveexec_b64 s[50:51], s[54:55]
	s_cbranch_execz .LBB0_1496
	s_waitcnt vmcnt(2)
	ds_write_b128 v101, v[32:35]
	ds_write_b128 v102, v[28:31]
	ds_write_b128 v103, v[36:39]
	s_and_saveexec_b64 s[54:55], s[44:45]
	ds_write_b128 v116, v[40:43]
	s_or_b64 exec, exec, s[54:55]
	ds_write_b128 v101, v[44:47] offset:13056
	ds_write_b128 v102, v[48:51] offset:13056
	ds_write_b128 v103, v[52:55] offset:13056
	s_and_b64 exec, exec, s[48:49]
	ds_write_b128 v116, v[56:59] offset:13056
